# phase 11 ticket loop: next tile's ticket fetched at the top of the current tile (atomic parked in a spare VGPR), latch only broadcasts it, on top of v_p11dyn
# baseline (speedup 1.0000x reference)
.LBB0_767:
	s_or_b64 exec, exec, s[10:11]
	v_cmp_eq_u32_e32 vcc, 0, v220
	s_and_saveexec_b64 s[10:11], vcc
	v_mov_b32_e32 v2, 0x10608
	ds_write_b32 v2, v253
	s_waitcnt lgkmcnt(0)
	s_or_b64 exec, exec, s[10:11]
	s_barrier
	v_mov_b32_e32 v1, 0x10608
	ds_read_b32 v1, v1
	s_waitcnt lgkmcnt(0)
	s_nop 1
	v_readfirstlane_b32 s4, v1
	s_nop 3
	s_lshl_b32 s4, s4, 3
	s_and_b32 s10, s2, 7
	s_or_b32 s4, s4, s10
	s_cmpk_lt_i32 s4, 0x880
	s_cbranch_scc0 .LBB0_962
.LBB0_768:
	v_cmp_eq_u32_e32 vcc, 0, v220
	s_and_saveexec_b64 s[10:11], vcc
	s_and_b32 s12, s2, 7
	s_lshl_b32 s12, s12, 6
	s_add_i32 s12, s12, 32
	v_mov_b32_e32 v2, s12
	v_mov_b32_e32 v253, 1
	global_atomic_add v253, v2, v253, s[100:101] sc0
	s_or_b64 exec, exec, s[10:11]
	s_ashr_i32 s10, s4, 3
	s_mul_hi_i32 s11, s10, 0x78787879
	s_lshr_b32 s12, s11, 31
	s_ashr_i32 s11, s11, 3
	s_add_i32 s11, s11, s12
	s_mul_i32 s12, s11, 17
	s_sub_i32 s10, s10, s12
	s_lshl_b32 s12, s4, 8
	s_lshl_b32 s11, s11, 11
	s_and_b32 s12, s12, 0x700
	s_or_b32 s12, s11, s12
	s_ashr_i32 s13, s12, 31
	s_lshl_b32 s10, s10, 7
	s_lshl_b64 s[14:15], s[12:13], 11
	s_add_u32 s14, s6, s14
	s_addc_u32 s15, s7, s15
	s_ashr_i32 s11, s10, 31
	v_mov_b32_e32 v36, v220
	s_lshl_b64 s[16:17], s[10:11], 11
	s_add_u32 s16, s8, s16
	v_ashrrev_i32_e32 v26, 2, v36
	v_ashrrev_i32_e32 v27, 31, v26
	s_addc_u32 s17, s9, s17
	v_lshlrev_b64 v[0:1], 11, v[26:27]
	v_lshlrev_b32_e32 v4, 4, v36
	v_lshl_add_u64 v[2:3], s[16:17], 0, v[0:1]
	v_lshl_add_u64 v[0:1], s[14:15], 0, v[0:1]
	v_and_b32_e32 v152, 48, v4
	v_lshl_add_u64 v[154:155], v[0:1], 0, v[152:153]
	v_add_co_u32_e32 v28, vcc, s38, v154
	v_lshl_add_u64 v[156:157], v[2:3], 0, v[152:153]
	s_nop 0
	v_addc_co_u32_e32 v29, vcc, 0, v155, vcc
	v_add_co_u32_e32 v30, vcc, s39, v154
	global_load_dwordx4 v[2:5], v[154:155], off
	s_nop 0
	v_addc_co_u32_e32 v31, vcc, 0, v155, vcc
	v_add_co_u32_e32 v32, vcc, s40, v154
	global_load_dwordx4 v[6:9], v[28:29], off
	s_nop 0
	v_addc_co_u32_e32 v33, vcc, 0, v155, vcc
	v_add_co_u32_e32 v34, vcc, s38, v156
	global_load_dwordx4 v[10:13], v[30:31], off
	s_nop 0
	v_addc_co_u32_e32 v35, vcc, 0, v157, vcc
	global_load_dwordx4 v[14:17], v[32:33], off
	global_load_dwordx4 v[18:21], v[156:157], off
	global_load_dwordx4 v[22:25], v[34:35], off
	global_load_dwordx4 v[120:123], v[154:155], off offset:64
	global_load_dwordx4 v[128:131], v[28:29], off offset:64
	global_load_dwordx4 v[132:135], v[30:31], off offset:64
	global_load_dwordx4 v[136:139], v[32:33], off offset:64
	global_load_dwordx4 v[124:127], v[156:157], off offset:64
	global_load_dwordx4 v[140:143], v[34:35], off offset:64
	v_lshrrev_b32_e32 v1, 4, v36
	v_lshrrev_b32_e32 v27, 2, v36
	v_sub_u32_e32 v39, 0, v1
	v_sub_u32_e32 v27, 0, v27
	v_and_b32_e32 v37, 0x3ffff8f, v36
	v_lshlrev_b32_e32 v38, 6, v36
	v_xor_b32_e32 v36, v36, v39
	v_xor_b32_e32 v1, v1, v27
	v_lshlrev_b32_e32 v27, 4, v36
	v_lshlrev_b32_e32 v1, 4, v1
	v_and_b32_e32 v40, 0x1000, v38
	v_and_b32_e32 v27, 48, v27
	v_and_b32_e32 v1, 48, v1
	v_and_b32_e32 v41, 0x3c0, v38
	v_and_b32_e32 v38, 0xffffe3c0, v38
	v_lshl_add_u32 v37, v37, 6, v166
	v_lshl_or_b32 v152, v26, 6, v27
	v_or_b32_e32 v26, v1, v40
	s_mov_b32 s11, -2
	s_mov_b32 s13, s35
	v_mov_b32_e32 v0, 0
	v_or3_b32 v168, v40, v41, v1
	v_add_u32_e32 v169, v1, v38
	v_add_u32_e32 v170, v1, v37
	v_add_u32_e32 v171, v26, v41
	v_lshl_add_u64 v[158:159], v[154:155], 0, s[24:25]
	v_lshl_add_u64 v[160:161], v[154:155], 0, s[28:29]
	v_lshl_add_u64 v[162:163], v[154:155], 0, s[30:31]
	v_lshl_add_u64 v[164:165], v[156:157], 0, s[24:25]
	v_mov_b32_e32 v1, v153
	v_mov_b32_e32 v26, v153
	v_mov_b32_e32 v27, v153
	v_mov_b32_e32 v28, 0
	v_mov_b32_e32 v29, v153
	v_mov_b32_e32 v30, v153
	v_mov_b32_e32 v31, v153
	v_mov_b32_e32 v32, 0
	v_mov_b32_e32 v33, v153
	v_mov_b32_e32 v34, v153
	v_mov_b32_e32 v35, v153
	v_mov_b32_e32 v36, 0
	v_mov_b32_e32 v37, v153
	v_mov_b32_e32 v38, v153
	v_mov_b32_e32 v39, v153
	v_mov_b32_e32 v40, 0
	v_mov_b32_e32 v41, v153
	v_mov_b32_e32 v42, v153
	v_mov_b32_e32 v43, v153
	v_mov_b32_e32 v44, 0
	s_waitcnt vmcnt(11)
	ds_write_b128 v152, v[2:5]
	s_waitcnt vmcnt(10)
	ds_write_b128 v152, v[6:9] offset:4096
	s_waitcnt vmcnt(9)
	ds_write_b128 v152, v[10:13] offset:8192
	s_waitcnt vmcnt(8)
	ds_write_b128 v152, v[14:17] offset:12288
	s_waitcnt vmcnt(7)
	ds_write_b128 v152, v[18:21] offset:32768
	s_waitcnt vmcnt(6)
	ds_write_b128 v152, v[22:25] offset:36864
	v_mov_b32_e32 v2, v153
	v_mov_b32_e32 v3, v153
	v_mov_b32_e32 v4, 0
	v_mov_b32_e32 v5, v153
	v_mov_b32_e32 v6, v153
	v_mov_b32_e32 v7, v153
	v_mov_b32_e32 v8, 0
	v_mov_b32_e32 v9, v153
	v_mov_b32_e32 v10, v153
	v_mov_b32_e32 v11, v153
	v_mov_b32_e32 v12, 0
	v_mov_b32_e32 v13, v153
	v_mov_b32_e32 v14, v153
	v_mov_b32_e32 v15, v153
	v_mov_b32_e32 v16, 0
	v_mov_b32_e32 v17, v153
	v_mov_b32_e32 v18, v153
	v_mov_b32_e32 v19, v153
	v_mov_b32_e32 v20, 0
	v_mov_b32_e32 v21, v153
	v_mov_b32_e32 v22, v153
	v_mov_b32_e32 v23, v153
	v_mov_b32_e32 v24, 0
	v_mov_b32_e32 v25, v153
	v_mov_b32_e32 v45, v153
	v_mov_b32_e32 v46, v153
	v_mov_b32_e32 v47, v153
	v_mov_b32_e32 v48, 0
	v_mov_b32_e32 v49, v153
	v_mov_b32_e32 v50, v153
	v_mov_b32_e32 v51, v153
	v_mov_b32_e32 v52, 0
	v_mov_b32_e32 v53, v153
	v_mov_b32_e32 v54, v153
	v_mov_b32_e32 v55, v153
	v_mov_b32_e32 v56, 0
	v_mov_b32_e32 v57, v153
	v_mov_b32_e32 v58, v153
	v_mov_b32_e32 v59, v153
	v_mov_b32_e32 v60, 0
	v_mov_b32_e32 v61, v153
	v_mov_b32_e32 v62, v153
	v_mov_b32_e32 v63, v153
	v_mov_b32_e32 v64, 0
	v_mov_b32_e32 v65, v153
	v_mov_b32_e32 v66, v153
	v_mov_b32_e32 v67, v153
	v_mov_b32_e32 v68, 0
	v_mov_b32_e32 v69, v153
	v_mov_b32_e32 v70, v153
	v_mov_b32_e32 v71, v153
	v_mov_b32_e32 v72, 0
	v_mov_b32_e32 v73, v153
	v_mov_b32_e32 v74, v153
	v_mov_b32_e32 v75, v153
	v_mov_b32_e32 v76, 0
	v_mov_b32_e32 v77, v153
	v_mov_b32_e32 v78, v153
	v_mov_b32_e32 v79, v153
	v_mov_b32_e32 v80, 0
	v_mov_b32_e32 v81, v153
	v_mov_b32_e32 v82, v153
	v_mov_b32_e32 v83, v153
	v_mov_b32_e32 v84, 0
	v_mov_b32_e32 v85, v153
	v_mov_b32_e32 v86, v153
	v_mov_b32_e32 v87, v153
	v_mov_b32_e32 v88, 0
	v_mov_b32_e32 v89, v153
	v_mov_b32_e32 v90, v153
	v_mov_b32_e32 v91, v153
	v_mov_b32_e32 v92, 0
	v_mov_b32_e32 v93, v153
	v_mov_b32_e32 v94, v153
	v_mov_b32_e32 v95, v153
	v_mov_b32_e32 v96, 0
	v_mov_b32_e32 v97, v153
	v_mov_b32_e32 v98, v153
	v_mov_b32_e32 v99, v153
	v_mov_b32_e32 v100, 0
	v_mov_b32_e32 v101, v153
	v_mov_b32_e32 v102, v153
	v_mov_b32_e32 v103, v153
	v_mov_b32_e32 v104, 0
	v_mov_b32_e32 v105, v153
	v_mov_b32_e32 v106, v153
	v_mov_b32_e32 v107, v153
	v_mov_b32_e32 v108, 0
	v_mov_b32_e32 v109, v153
	v_mov_b32_e32 v110, v153
	v_mov_b32_e32 v111, v153
	v_mov_b32_e32 v112, 0
	v_mov_b32_e32 v113, v153
	v_mov_b32_e32 v114, v153
	v_mov_b32_e32 v115, v153
	v_mov_b32_e32 v116, 0
	v_mov_b32_e32 v117, v153
	v_mov_b32_e32 v118, v153
	v_mov_b32_e32 v119, v153
	v_mov_b32_e32 v144, 0
	v_mov_b32_e32 v145, v153
	v_mov_b32_e32 v146, v153
	v_mov_b32_e32 v147, v153
	v_mov_b32_e32 v148, 0
	v_mov_b32_e32 v149, v153
	v_mov_b32_e32 v150, v153
	v_mov_b32_e32 v151, v153
	s_waitcnt lgkmcnt(0)
	s_add_i32 s14, s13, 64
	s_min_u32 s15, s14, 0x3e0
	s_lshl_b32 s34, s15, 1
	v_lshl_add_u64 v[172:173], v[154:155], 0, s[34:35]
	v_lshl_add_u64 v[176:177], v[158:159], 0, s[34:35]
	v_lshl_add_u64 v[180:181], v[160:161], 0, s[34:35]
	v_lshl_add_u64 v[184:185], v[162:163], 0, s[34:35]
	v_lshl_add_u64 v[188:189], v[156:157], 0, s[34:35]
	v_lshl_add_u64 v[192:193], v[164:165], 0, s[34:35]
